# MIX work queues: one snapshot of the 8 counters when the own queue is empty, exhausted queues are skipped without an atomic
# speedup vs baseline: 1.0022x; 1.0022x over previous
; DI unsigned xb_xcc_id() { return (unsigned)__builtin_amdgcn_s_getreg((3 << 11) | 20) & 0xFu; }
; DI void run_phase(const Params& pin, int ph, unsigned char* lds, int* s_item) {
;     ...
;     case 4: {
;       unsigned* ctr = (unsigned*)(p.ws + OFF_CTR) + ps * 8;
;       const int myx = (int)(xb_xcc_id() & 7u);
;       for (int dx = 0; dx < 8; ++dx) {
;         const int x = (myx + dx) & 7;
;         for (;;) {
;           if (tid == 0) *s_item = (int)atomicAdd(ctr + x, 1u);
;           __syncthreads();
;           const int j = *s_item;
;           __syncthreads();
;           if (j >= 193) break;
;           if (j == 0) scan_item(p, x, lds);
;           else {
;             const int g = (j - 1) / 3, k = (j - 1) % 3;
;             if (k < 2) diffmap_item(p, l, x >> 1, x & 1, 127 - 2 * g - k, lds);
;             else mla_item(p, l, x >> 1, 127 - 2 * g - (x & 1), lds);
;           }
;         }
;       }
.LBB0_350:
	s_cmp_lg_u32 s4, 0
	s_cbranch_scc1 .Lq_have
	s_and_saveexec_b64 s[0:1], s[38:39]
	s_cbranch_execz .Lq_s1
	v_readlane_b32 s6, v254, 58
	v_readlane_b32 s7, v254, 59
	s_nop 4
	global_load_dwordx4 v[2:5], v1, s[6:7] sc0 sc1
	global_load_dwordx4 v[6:9], v1, s[6:7] offset:16 sc0 sc1
	v_mov_b32_e32 v0, 0
	s_waitcnt vmcnt(0)
	v_cmp_gt_u32_e32 vcc, 0xc1, v2
	s_nop 1
	v_cndmask_b32_e64 v10, 0, 1, vcc
	v_lshl_or_b32 v0, v10, 0, v0
	v_cmp_gt_u32_e32 vcc, 0xc1, v3
	s_nop 1
	v_cndmask_b32_e64 v10, 0, 1, vcc
	v_lshl_or_b32 v0, v10, 1, v0
	v_cmp_gt_u32_e32 vcc, 0xc1, v4
	s_nop 1
	v_cndmask_b32_e64 v10, 0, 1, vcc
	v_lshl_or_b32 v0, v10, 2, v0
	v_cmp_gt_u32_e32 vcc, 0xc1, v5
	s_nop 1
	v_cndmask_b32_e64 v10, 0, 1, vcc
	v_lshl_or_b32 v0, v10, 3, v0
	v_cmp_gt_u32_e32 vcc, 0xc1, v6
	s_nop 1
	v_cndmask_b32_e64 v10, 0, 1, vcc
	v_lshl_or_b32 v0, v10, 4, v0
	v_cmp_gt_u32_e32 vcc, 0xc1, v7
	s_nop 1
	v_cndmask_b32_e64 v10, 0, 1, vcc
	v_lshl_or_b32 v0, v10, 5, v0
	v_cmp_gt_u32_e32 vcc, 0xc1, v8
	s_nop 1
	v_cndmask_b32_e64 v10, 0, 1, vcc
	v_lshl_or_b32 v0, v10, 6, v0
	v_cmp_gt_u32_e32 vcc, 0xc1, v9
	s_nop 1
	v_cndmask_b32_e64 v10, 0, 1, vcc
	v_lshl_or_b32 v0, v10, 7, v0
	ds_write_b32 v1, v0 offset:63504
.Lq_s1:
	s_or_b64 exec, exec, s[0:1]
	s_waitcnt lgkmcnt(0)
	s_barrier
	ds_read_b32 v0, v1 offset:63504
	s_waitcnt lgkmcnt(0)
	s_barrier
	v_readfirstlane_b32 s0, v0
	s_nop 3
	v_writelane_b32 v255, s0, 62
	s_nop 1
.Lq_have:
	v_readlane_b32 s0, v255, 62
	v_readlane_b32 s1, v254, 60
.Lq_next:
	s_add_i32 s4, s4, 1
	s_add_i32 s56, s56, 1
	s_xor_b64 s[2:3], s[2:3], -1
	s_cmp_eq_u32 s4, 8
	s_cbranch_scc1 .LBB0_444
	s_add_i32 s6, s4, s1
	s_and_b32 s6, s6, 7
	s_bitcmp1_b32 s0, s6
	s_cbranch_scc0 .Lq_next
